# dependency-counter wait loops poll with no back-off (s_sleep 1 -> 0 at the 22 sites)
# speedup vs baseline: 1.0081x; 1.0013x over previous
.LBB0_806:
	global_load_dword v4, v1, s[6:7] sc1
	s_mov_b64 s[18:19], -1
	s_waitcnt vmcnt(0)
	v_cmp_lt_u32_e32 vcc, 21, v4
	s_cbranch_vccnz .LBB0_805
	s_sleep 0
	s_memrealtime s[18:19]
	s_waitcnt lgkmcnt(0)
	s_sub_u32 s18, s18, s10
	s_subb_u32 s19, s19, s11
	v_cmp_gt_u64_e64 s[18:19], s[18:19], v[2:3]
	s_branch .LBB0_805

.LBB0_837:
	global_load_dword v4, v1, s[8:9] sc1
	s_mov_b64 s[18:19], -1
	s_waitcnt vmcnt(0)
	v_cmp_lt_u32_e32 vcc, 3, v4
	s_cbranch_vccnz .LBB0_836
	s_sleep 0
	s_memrealtime s[18:19]
	s_waitcnt lgkmcnt(0)
	s_sub_u32 s18, s18, s10
	s_subb_u32 s19, s19, s11
	v_cmp_gt_u64_e64 s[18:19], s[18:19], v[2:3]
	s_branch .LBB0_836

.LBB0_871:
	global_load_dword v4, v1, s[10:11] sc1
	s_mov_b64 s[12:13], -1
	s_waitcnt vmcnt(0)
	v_cmp_lt_u32_e32 vcc, 3, v4
	s_cbranch_vccnz .LBB0_870
	s_sleep 0
	s_memrealtime s[4:5]
	s_waitcnt lgkmcnt(0)
	s_sub_u32 s4, s4, s8
	s_subb_u32 s5, s5, s9
	v_cmp_gt_u64_e64 s[12:13], s[4:5], v[2:3]
	s_branch .LBB0_870

.LBB0_999:
	global_load_dword v4, v1, s[8:9] sc1
	s_mov_b64 s[12:13], -1
	s_waitcnt vmcnt(0)
	v_cmp_lt_u32_e32 vcc, 3, v4
	s_cbranch_vccnz .LBB0_998
	s_sleep 0
	s_memrealtime s[12:13]
	s_waitcnt lgkmcnt(0)
	s_sub_u32 s12, s12, s6
	s_subb_u32 s13, s13, s7
	v_cmp_gt_u64_e64 s[12:13], s[12:13], v[2:3]
	s_branch .LBB0_998

.LBB0_2902:
	s_nop 3
	global_load_dword v4, v1, s[12:13] sc1
	s_mov_b64 s[10:11], -1
	s_waitcnt vmcnt(0)
	v_cmp_lt_u32_e32 vcc, s2, v4
	s_cbranch_vccnz .LBB0_2901
	s_sleep 0
	s_memrealtime s[10:11]
	s_waitcnt lgkmcnt(0)
	s_sub_u32 s10, s10, s8
	s_subb_u32 s11, s11, s9
	v_cmp_gt_u64_e64 s[10:11], s[10:11], v[2:3]
	s_branch .LBB0_2901

.LBB0_2932:
	global_load_dword v4, v1, s[8:9] sc1
	s_mov_b64 s[12:13], -1
	s_waitcnt vmcnt(0)
	v_cmp_lt_u32_e32 vcc, 3, v4
	s_cbranch_vccnz .LBB0_2931
	s_sleep 0
	s_memrealtime s[2:3]
	s_waitcnt lgkmcnt(0)
	s_sub_u32 s2, s2, s10
	s_subb_u32 s3, s3, s11
	v_cmp_gt_u64_e64 s[12:13], s[2:3], v[2:3]
	s_branch .LBB0_2931

.LBB0_2941:
	v_readlane_b32 s10, v228, 17
	v_readlane_b32 s11, v228, 18
	s_nop 4
	global_load_dword v4, v1, s[10:11] sc1
	s_mov_b64 s[10:11], -1
	s_waitcnt vmcnt(0)
	v_cmp_lt_u32_e32 vcc, s2, v4
	s_cbranch_vccnz .LBB0_2940
	s_sleep 0
	s_memrealtime s[10:11]
	s_waitcnt lgkmcnt(0)
	s_sub_u32 s10, s10, s8
	s_subb_u32 s11, s11, s9
	v_cmp_gt_u64_e64 s[10:11], s[10:11], v[2:3]
	s_branch .LBB0_2940

.LBB0_3159:
	global_load_dword v4, v1, s[6:7] sc1
	s_mov_b64 s[24:25], -1
	s_waitcnt vmcnt(0)
	v_cmp_lt_u32_e32 vcc, 21, v4
	s_cbranch_vccnz .LBB0_3158
	s_sleep 0
	s_memrealtime s[24:25]
	s_waitcnt lgkmcnt(0)
	s_sub_u32 s24, s24, s10
	s_subb_u32 s25, s25, s11
	v_cmp_gt_u64_e64 s[24:25], s[24:25], v[2:3]
	s_branch .LBB0_3158

.LBB0_3189:
	global_load_dword v4, v1, s[8:9] sc1
	s_mov_b64 s[24:25], -1
	s_waitcnt vmcnt(0)
	v_cmp_lt_u32_e32 vcc, 3, v4
	s_cbranch_vccnz .LBB0_3188
	s_sleep 0
	s_memrealtime s[24:25]
	s_waitcnt lgkmcnt(0)
	s_sub_u32 s24, s24, s10
	s_subb_u32 s25, s25, s11
	v_cmp_gt_u64_e64 s[24:25], s[24:25], v[2:3]
	s_branch .LBB0_3188

.LBB0_3336:
	global_load_dword v4, v1, s[8:9] sc1
	s_mov_b64 s[16:17], -1
	s_waitcnt vmcnt(0)
	v_cmp_lt_u32_e32 vcc, 3, v4
	s_cbranch_vccnz .LBB0_3335
	s_sleep 0
	s_memrealtime s[16:17]
	s_waitcnt lgkmcnt(0)
	s_sub_u32 s16, s16, s6
	s_subb_u32 s17, s17, s7
	v_cmp_gt_u64_e64 s[16:17], s[16:17], v[2:3]
	s_branch .LBB0_3335

.LBB0_3413:
	global_load_dword v4, v1, s[6:7] sc1
	s_mov_b64 s[20:21], -1
	s_waitcnt vmcnt(0)
	v_cmp_lt_u32_e32 vcc, 21, v4
	s_cbranch_vccnz .LBB0_3412
	s_sleep 0
	s_memrealtime s[20:21]
	s_waitcnt lgkmcnt(0)
	s_sub_u32 s20, s20, s10
	s_subb_u32 s21, s21, s11
	v_cmp_gt_u64_e64 s[20:21], s[20:21], v[2:3]
	s_branch .LBB0_3412

.LBB0_3444:
	global_load_dword v4, v1, s[8:9] sc1
	s_mov_b64 s[20:21], -1
	s_waitcnt vmcnt(0)
	v_cmp_lt_u32_e32 vcc, 3, v4
	s_cbranch_vccnz .LBB0_3443
	s_sleep 0
	s_memrealtime s[20:21]
	s_waitcnt lgkmcnt(0)
	s_sub_u32 s20, s20, s10
	s_subb_u32 s21, s21, s11
	v_cmp_gt_u64_e64 s[20:21], s[20:21], v[2:3]
	s_branch .LBB0_3443

.LBB0_5548:
	v_readlane_b32 s10, v228, 29
	v_readlane_b32 s11, v228, 30
	s_nop 4
	global_load_dword v4, v1, s[10:11] sc1
	s_mov_b64 s[10:11], -1
	s_waitcnt vmcnt(0)
	v_cmp_lt_u32_e32 vcc, s2, v4
	s_cbranch_vccnz .LBB0_5547
	s_sleep 0
	s_memrealtime s[10:11]
	s_waitcnt lgkmcnt(0)
	s_sub_u32 s10, s10, s8
	s_subb_u32 s11, s11, s9
	v_cmp_gt_u64_e64 s[10:11], s[10:11], v[2:3]
	s_branch .LBB0_5547

.LBB0_5766:
	global_load_dword v4, v1, s[6:7] sc1
	s_mov_b64 s[12:13], -1
	s_waitcnt vmcnt(0)
	v_cmp_lt_u32_e32 vcc, 21, v4
	s_cbranch_vccnz .LBB0_5765
	s_sleep 0
	s_memrealtime s[12:13]
	s_waitcnt lgkmcnt(0)
	s_sub_u32 s12, s12, s10
	s_subb_u32 s13, s13, s11
	v_cmp_gt_u64_e64 s[12:13], s[12:13], v[2:3]
	s_branch .LBB0_5765

.LBB0_5796:
	global_load_dword v4, v1, s[8:9] sc1
	s_mov_b64 s[12:13], -1
	s_waitcnt vmcnt(0)
	v_cmp_lt_u32_e32 vcc, 3, v4
	s_cbranch_vccnz .LBB0_5795
	s_sleep 0
	s_memrealtime s[12:13]
	s_waitcnt lgkmcnt(0)
	s_sub_u32 s12, s12, s10
	s_subb_u32 s13, s13, s11
	v_cmp_gt_u64_e64 s[12:13], s[12:13], v[2:3]
	s_branch .LBB0_5795

.LBB0_5943:
	global_load_dword v4, v1, s[8:9] sc1
	s_mov_b64 s[4:5], -1
	s_waitcnt vmcnt(0)
	v_cmp_lt_u32_e32 vcc, 3, v4
	s_cbranch_vccnz .LBB0_5942
	s_sleep 0
	s_memrealtime s[4:5]
	s_waitcnt lgkmcnt(0)
	s_sub_u32 s4, s4, s2
	s_subb_u32 s5, s5, s3
	v_cmp_gt_u64_e64 s[4:5], s[4:5], v[2:3]
	s_branch .LBB0_5942
